# hand-written rmsnorm phases (norm1, norm2, final): batched loads + DPP reduction instead of serialized per-column round trips
# speedup vs baseline: 1.0153x; 1.0153x over previous
.LBB0_81:
	s_xor_b64 s[6:7], s[4:5], -1
	v_writelane_b32 v252, s6, 9
	s_mov_b32 s34, s30
	s_mul_i32 s30, s30, 0xf000
	v_writelane_b32 v252, s7, 10
	s_mov_b32 s6, 0
	v_mov_b32 v1, v148
	v_readlane_b32 s7, v253, 8
	v_lshrrev_b32_e32 v0, 6, v1
	v_writelane_b32 v252, s34, 11
	v_or_b32_e32 v32, s7, v0
	v_cmp_gt_i32_e32 vcc, s33, v32
	v_writelane_b32 v252, s35, 12
	v_writelane_b32 v252, s30, 13
	s_nop 1
	v_writelane_b32 v252, s31, 14
	s_and_saveexec_b64 s[38:39], vcc
	s_cbranch_execz .LBB0_172
	s_ashr_i32 s7, s6, 31
	v_readlane_b32 s30, v253, 3
	v_readlane_b32 s31, v253, 4
	s_add_u32 s30, s30, s6
	s_addc_u32 s31, s31, s7
	s_load_dwordx2 s[34:35], s[30:31], 0x100
	v_readlane_b32 s36, v252, 11
	s_load_dwordx2 s[30:31], s[30:31], 0x50
	v_readlane_b32 s37, v252, 12
	v_readlane_b32 s40, v252, 13
	s_waitcnt lgkmcnt(0)
	s_add_u32 s42, s34, 0xc000000
	s_addc_u32 s43, s35, 0
	s_add_u32 s44, s34, 0x12000000
	s_addc_u32 s45, s35, 0
	s_add_u32 s46, s34, 0x2fc80100
	s_addc_u32 s47, s35, 0
	s_lshl_b32 s88, s36, 11
	s_lshl_b64 s[36:37], s[88:89], 2
	v_readlane_b32 s41, v252, 14
	s_add_u32 s30, s30, s36
	s_mov_b32 s36, s40
	s_mov_b32 s41, s89
	s_addc_u32 s31, s31, s37
	v_writelane_b32 v252, s36, 13
	v_lshlrev_b32_e32 v1, 2, v1
	v_and_b32_e32 v34, 0xfc, v1
	v_writelane_b32 v252, s37, 14
	s_lshl_b64 s[36:37], s[40:41], 2
	s_add_u32 s36, s34, s36
	v_lshlrev_b32_e32 v128, 2, v34
	s_addc_u32 s37, s35, s37
	v_lshl_add_u64 v[2:3], s[34:35], 0, v[128:129]
	s_mov_b64 s[34:35], 0x21000000
	v_cmp_lt_i32_e32 vcc, v159, v153
	s_waitcnt vmcnt(34)
	v_lshl_add_u64 v[36:37], v[2:3], 0, s[34:35]
	s_waitcnt vmcnt(33)
	v_or_b32_e32 v42, 0x400, v34
	v_cndmask_b32_e32 v2, v152, v159, vcc
	v_cmp_lt_i32_e32 vcc, v158, v153
	v_lshlrev_b32_e32 v35, 2, v2
	v_lshl_add_u64 v[40:41], s[30:31], 0, v[128:129]
	v_cndmask_b32_e32 v2, v152, v158, vcc
	v_cmp_lt_i32_e32 vcc, v157, v153
	v_lshlrev_b32_e32 v43, 2, v2
	v_lshlrev_b32_e32 v128, 2, v42
	v_cndmask_b32_e32 v2, v152, v157, vcc
	v_cmp_lt_i32_e32 vcc, v156, v153
	s_waitcnt vmcnt(32)
	v_lshlrev_b32_e32 v47, 2, v2
	v_or_b32_e32 v46, 0x500, v34
	v_cndmask_b32_e32 v2, v152, v156, vcc
	v_cmp_lt_i32_e32 vcc, v155, v153
	s_waitcnt vmcnt(0)
	v_lshlrev_b32_e32 v51, 2, v2
	v_lshl_add_u64 v[44:45], s[30:31], 0, v[128:129]
	v_cndmask_b32_e32 v2, v152, v155, vcc
	v_cmp_lt_i32_e32 vcc, v154, v153
	v_lshlrev_b32_e32 v128, 2, v46
	v_or_b32_e32 v50, 0x600, v34
	v_lshlrev_b32_e32 v78, 2, v2
	v_cndmask_b32_e32 v2, v152, v154, vcc
	v_or_b32_e32 v38, 0x700, v1
	v_mov_b32_e32 v39, v129
	v_lshl_add_u64 v[48:49], s[30:31], 0, v[128:129]
	v_lshlrev_b32_e32 v128, 2, v50
	s_add_u32 s48, s36, 0x28b00000
	v_lshlrev_b32_e32 v79, 2, v2
	v_or_b32_e32 v2, 0x100, v34
	v_or_b32_e32 v4, 0x200, v34
	v_or_b32_e32 v6, 0x300, v34
	v_lshl_add_u64 v[52:53], s[30:31], 0, v[128:129]
	v_lshl_add_u64 v[54:55], v[38:39], 2, s[30:31]
	v_ashrrev_i32_e32 v33, 31, v32
	v_readlane_b32 s30, v254, 44
	s_addc_u32 s49, s37, 0
	v_lshlrev_b64 v[56:57], 13, v[32:33]
	v_lshl_add_u32 v80, v0, 8, s30
	s_mov_b64 s[50:51], 0
	v_lshlrev_b32_e32 v58, 2, v2
	v_lshlrev_b32_e32 v60, 2, v4
	v_lshlrev_b32_e32 v62, 2, v6
	v_readlane_b32 s54, v253, 8
	v_lshrrev_b32_e32 v1, 6, v148
	v_readlane_b32 s55, v253, 1
	v_readfirstlane_b32 s40, v1
	v_readlane_b32 s82, v253, 3
	v_readlane_b32 s83, v253, 4
	s_add_u32 s54, s54, s40
	s_lshl_b32 s55, s55, 3
	s_load_dwordx2 s[70:71], s[82:83], 0x100
	s_load_dwordx2 s[72:73], s[82:83], 0x50
	s_load_dwordx2 s[74:75], s[82:83], 0x0
	s_load_dwordx2 s[76:77], s[82:83], 0x8
	v_readlane_b32 s84, v252, 11
	v_and_b32_e32 v0, 63, v148
	v_lshlrev_b32_e32 v1, 4, v0
	v_lshlrev_b32_e32 v2, 3, v0
	v_and_b32_e32 v3, 7, v0
	v_lshlrev_b32_e32 v3, 2, v3
	v_add_u32_e32 v7, 0x1000, v1
	s_lshl_b32 s40, s84, 13
	s_waitcnt lgkmcnt(0)
	s_add_u32 s72, s72, s40
	s_addc_u32 s73, s73, 0
	s_add_u32 s78, s70, 0x21000000
	s_addc_u32 s79, s71, 0
	s_cmp_lt_u32 s54, 0x3000
	s_cbranch_scc0 .Lnr1_done
.Lnr1_row:
	s_lshl_b32 s40, s54, 13
	s_add_u32 s64, s42, s40
	s_addc_u32 s65, s43, 0
	s_cmp_lg_u32 s84, 0
	s_cbranch_scc1 .Lnr1_tmap
	s_sub_u32 s41, s40, 0x2000000
	s_cmp_lt_u32 s54, 0x1000
	s_cselect_b32 s40, s40, s41
	s_cselect_b32 s82, s74, s76
	s_cselect_b32 s83, s75, s77
	s_add_u32 s82, s82, s40
	s_addc_u32 s83, s83, 0
	global_load_dwordx4 v[8:11], v1, s[82:83] nt
	global_load_dwordx4 v[12:15], v1, s[82:83] offset:1024 nt
	global_load_dwordx4 v[16:19], v1, s[82:83] offset:2048 nt
	global_load_dwordx4 v[20:23], v1, s[82:83] offset:3072 nt
	global_load_dwordx4 v[24:27], v7, s[82:83] nt
	global_load_dwordx4 v[28:31], v7, s[82:83] offset:1024 nt
	global_load_dwordx4 v[32:35], v7, s[82:83] offset:2048 nt
	global_load_dwordx4 v[36:39], v7, s[82:83] offset:3072 nt
	s_waitcnt vmcnt(0)
	global_store_dwordx4 v1, v[8:11], s[64:65]
	global_store_dwordx4 v1, v[12:15], s[64:65] offset:1024
	global_store_dwordx4 v1, v[16:19], s[64:65] offset:2048
	global_store_dwordx4 v1, v[20:23], s[64:65] offset:3072
	global_store_dwordx4 v7, v[24:27], s[64:65]
	global_store_dwordx4 v7, v[28:31], s[64:65] offset:1024
	global_store_dwordx4 v7, v[32:35], s[64:65] offset:2048
	global_store_dwordx4 v7, v[36:39], s[64:65] offset:3072
	s_branch .Lnr1_common
.Lnr1_tmap:
	s_lshr_b32 s41, s54, 8
	s_lshl_b32 s41, s41, 5
	s_add_u32 s40, s46, s41
	s_addc_u32 s41, s47, 0
	global_load_dword v4, v3, s[40:41]
	global_load_dwordx4 v[8:11], v1, s[64:65]
	global_load_dwordx4 v[12:15], v1, s[64:65] offset:1024
	global_load_dwordx4 v[16:19], v1, s[64:65] offset:2048
	global_load_dwordx4 v[20:23], v1, s[64:65] offset:3072
	global_load_dwordx4 v[24:27], v7, s[64:65]
	global_load_dwordx4 v[28:31], v7, s[64:65] offset:1024
	global_load_dwordx4 v[32:35], v7, s[64:65] offset:2048
	global_load_dwordx4 v[36:39], v7, s[64:65] offset:3072
	s_waitcnt vmcnt(8)
	v_readlane_b32 s56, v4, 0
	v_readlane_b32 s57, v4, 1
	v_readlane_b32 s58, v4, 2
	v_readlane_b32 s59, v4, 3
	v_readlane_b32 s60, v4, 4
	v_readlane_b32 s61, v4, 5
	v_readlane_b32 s62, v4, 6
	v_readlane_b32 s63, v4, 7
	s_and_b32 s40, s54, 0xff
	s_cmp_lt_i32 s56, 0
	s_cbranch_scc1 .Lnr1_sl0
	s_lshl_b32 s41, s56, 8
	s_add_u32 s41, s41, s40
	s_lshl_b32 s41, s41, 10
	s_add_u32 s30, s78, s41
	s_addc_u32 s31, s79, 0
	global_load_dwordx4 v[40:43], v1, s[30:31]
.Lnr1_sl0:
	s_cmp_lt_i32 s57, 0
	s_cbranch_scc1 .Lnr1_sl1
	s_lshl_b32 s41, s57, 8
	s_add_u32 s41, s41, s40
	s_lshl_b32 s41, s41, 10
	s_add_u32 s30, s78, s41
	s_addc_u32 s31, s79, 0
	global_load_dwordx4 v[44:47], v1, s[30:31]
.Lnr1_sl1:
	s_cmp_lt_i32 s58, 0
	s_cbranch_scc1 .Lnr1_sl2
	s_lshl_b32 s41, s58, 8
	s_add_u32 s41, s41, s40
	s_lshl_b32 s41, s41, 10
	s_add_u32 s30, s78, s41
	s_addc_u32 s31, s79, 0
	global_load_dwordx4 v[48:51], v1, s[30:31]
.Lnr1_sl2:
	s_cmp_lt_i32 s59, 0
	s_cbranch_scc1 .Lnr1_sl3
	s_lshl_b32 s41, s59, 8
	s_add_u32 s41, s41, s40
	s_lshl_b32 s41, s41, 10
	s_add_u32 s30, s78, s41
	s_addc_u32 s31, s79, 0
	global_load_dwordx4 v[52:55], v1, s[30:31]
.Lnr1_sl3:
	s_cmp_lt_i32 s60, 0
	s_cbranch_scc1 .Lnr1_sl4
	s_lshl_b32 s41, s60, 8
	s_add_u32 s41, s41, s40
	s_lshl_b32 s41, s41, 10
	s_add_u32 s30, s78, s41
	s_addc_u32 s31, s79, 0
	global_load_dwordx4 v[56:59], v1, s[30:31]
.Lnr1_sl4:
	s_cmp_lt_i32 s61, 0
	s_cbranch_scc1 .Lnr1_sl5
	s_lshl_b32 s41, s61, 8
	s_add_u32 s41, s41, s40
	s_lshl_b32 s41, s41, 10
	s_add_u32 s30, s78, s41
	s_addc_u32 s31, s79, 0
	global_load_dwordx4 v[60:63], v1, s[30:31]
.Lnr1_sl5:
	s_cmp_lt_i32 s62, 0
	s_cbranch_scc1 .Lnr1_sl6
	s_lshl_b32 s41, s62, 8
	s_add_u32 s41, s41, s40
	s_lshl_b32 s41, s41, 10
	s_add_u32 s30, s78, s41
	s_addc_u32 s31, s79, 0
	global_load_dwordx4 v[64:67], v1, s[30:31]
.Lnr1_sl6:
	s_cmp_lt_i32 s63, 0
	s_cbranch_scc1 .Lnr1_sl7
	s_lshl_b32 s41, s63, 8
	s_add_u32 s41, s41, s40
	s_lshl_b32 s41, s41, 10
	s_add_u32 s30, s78, s41
	s_addc_u32 s31, s79, 0
	global_load_dwordx4 v[68:71], v1, s[30:31]
.Lnr1_sl7:
	s_waitcnt vmcnt(0)
	s_cmp_lt_i32 s56, 0
	s_cbranch_scc1 .Lnr1_sa0
	v_pk_add_f32 v[8:9], v[8:9], v[40:41]
	v_pk_add_f32 v[10:11], v[10:11], v[42:43]
	global_store_dwordx4 v1, v[8:11], s[64:65]
.Lnr1_sa0:
	s_cmp_lt_i32 s57, 0
	s_cbranch_scc1 .Lnr1_sa1
	v_pk_add_f32 v[12:13], v[12:13], v[44:45]
	v_pk_add_f32 v[14:15], v[14:15], v[46:47]
	global_store_dwordx4 v1, v[12:15], s[64:65] offset:1024
.Lnr1_sa1:
	s_cmp_lt_i32 s58, 0
	s_cbranch_scc1 .Lnr1_sa2
	v_pk_add_f32 v[16:17], v[16:17], v[48:49]
	v_pk_add_f32 v[18:19], v[18:19], v[50:51]
	global_store_dwordx4 v1, v[16:19], s[64:65] offset:2048
.Lnr1_sa2:
	s_cmp_lt_i32 s59, 0
	s_cbranch_scc1 .Lnr1_sa3
	v_pk_add_f32 v[20:21], v[20:21], v[52:53]
	v_pk_add_f32 v[22:23], v[22:23], v[54:55]
	global_store_dwordx4 v1, v[20:23], s[64:65] offset:3072
.Lnr1_sa3:
	s_cmp_lt_i32 s60, 0
	s_cbranch_scc1 .Lnr1_sa4
	v_pk_add_f32 v[24:25], v[24:25], v[56:57]
	v_pk_add_f32 v[26:27], v[26:27], v[58:59]
	global_store_dwordx4 v7, v[24:27], s[64:65]
.Lnr1_sa4:
	s_cmp_lt_i32 s61, 0
	s_cbranch_scc1 .Lnr1_sa5
	v_pk_add_f32 v[28:29], v[28:29], v[60:61]
	v_pk_add_f32 v[30:31], v[30:31], v[62:63]
	global_store_dwordx4 v7, v[28:31], s[64:65] offset:1024
.Lnr1_sa5:
	s_cmp_lt_i32 s62, 0
	s_cbranch_scc1 .Lnr1_sa6
	v_pk_add_f32 v[32:33], v[32:33], v[64:65]
	v_pk_add_f32 v[34:35], v[34:35], v[66:67]
	global_store_dwordx4 v7, v[32:35], s[64:65] offset:2048
.Lnr1_sa6:
	s_cmp_lt_i32 s63, 0
	s_cbranch_scc1 .Lnr1_sa7
	v_pk_add_f32 v[36:37], v[36:37], v[68:69]
	v_pk_add_f32 v[38:39], v[38:39], v[70:71]
	global_store_dwordx4 v7, v[36:39], s[64:65] offset:3072
.Lnr1_sa7:
.Lnr1_common:
	s_sub_u32 s41, s54, 0x1000
	s_lshr_b32 s41, s41, 11
	s_add_u32 s41, s41, 1
	s_mul_i32 s41, s41, 0xc000
	s_cmp_lt_u32 s54, 0x1000
	s_cselect_b32 s40, 0, s41
	s_add_u32 s80, s48, s40
	s_addc_u32 s81, s49, 0
	s_add_u32 s30, s80, 0x2000
	s_addc_u32 s31, s81, 0
	global_load_dwordx4 v[40:43], v1, s[72:73]
	global_load_dwordx4 v[56:59], v1, s[80:81]
	global_load_dwordx4 v[72:75], v1, s[30:31]
	global_load_dwordx4 v[44:47], v1, s[72:73] offset:1024
	global_load_dwordx4 v[60:63], v1, s[80:81] offset:1024
	global_load_dwordx4 v[76:79], v1, s[30:31] offset:1024
	global_load_dwordx4 v[48:51], v1, s[72:73] offset:2048
	global_load_dwordx4 v[64:67], v1, s[80:81] offset:2048
	global_load_dwordx4 v[80:83], v1, s[30:31] offset:2048
	global_load_dwordx4 v[52:55], v1, s[72:73] offset:3072
	global_load_dwordx4 v[68:71], v1, s[80:81] offset:3072
	global_load_dwordx4 v[88:91], v1, s[30:31] offset:3072
	s_lshl_b32 s40, s54, 12
	s_add_u32 s66, s44, s40
	s_addc_u32 s67, s45, 0
	v_pk_mul_f32 v[92:93], v[8:9], v[8:9]
	v_pk_fma_f32 v[92:93], v[10:11], v[10:11], v[92:93]
	v_pk_fma_f32 v[92:93], v[12:13], v[12:13], v[92:93]
	v_pk_fma_f32 v[92:93], v[14:15], v[14:15], v[92:93]
	v_pk_fma_f32 v[92:93], v[16:17], v[16:17], v[92:93]
	v_pk_fma_f32 v[92:93], v[18:19], v[18:19], v[92:93]
	v_pk_fma_f32 v[92:93], v[20:21], v[20:21], v[92:93]
	v_pk_fma_f32 v[92:93], v[22:23], v[22:23], v[92:93]
	v_pk_fma_f32 v[92:93], v[24:25], v[24:25], v[92:93]
	v_pk_fma_f32 v[92:93], v[26:27], v[26:27], v[92:93]
	v_pk_fma_f32 v[92:93], v[28:29], v[28:29], v[92:93]
	v_pk_fma_f32 v[92:93], v[30:31], v[30:31], v[92:93]
	v_pk_fma_f32 v[92:93], v[32:33], v[32:33], v[92:93]
	v_pk_fma_f32 v[92:93], v[34:35], v[34:35], v[92:93]
	v_pk_fma_f32 v[92:93], v[36:37], v[36:37], v[92:93]
	v_pk_fma_f32 v[92:93], v[38:39], v[38:39], v[92:93]
	v_add_f32_e32 v5, v92, v93
	s_nop 1
	v_add_f32_dpp v5, v5, v5 quad_perm:[1,0,3,2] row_mask:0xf bank_mask:0xf bound_ctrl:1
	s_nop 1
	v_add_f32_dpp v5, v5, v5 quad_perm:[2,3,0,1] row_mask:0xf bank_mask:0xf bound_ctrl:1
	s_nop 1
	v_add_f32_dpp v5, v5, v5 row_half_mirror row_mask:0xf bank_mask:0xf bound_ctrl:1
	s_nop 1
	v_add_f32_dpp v5, v5, v5 row_mirror row_mask:0xf bank_mask:0xf bound_ctrl:1
	s_nop 1
	v_readlane_b32 s40, v5, 0
	v_readlane_b32 s41, v5, 16
	v_readlane_b32 s56, v5, 32
	v_readlane_b32 s57, v5, 48
	s_nop 1
	v_mov_b32_e32 v5, s40
	v_add_f32_e32 v5, s41, v5
	v_add_f32_e32 v5, s56, v5
	v_add_f32_e32 v5, s57, v5
	v_mov_b32_e32 v6, 0x358637bd
	v_fmamk_f32 v5, v5, 0x3a000000, v6
	v_rsq_f32_e32 v6, v5
	s_movk_i32 s40, 0x7fff
	s_mov_b32 s41, 0xffff0000
	s_waitcnt vmcnt(9)
	v_pk_mul_f32 v[8:9], v[8:9], v[6:7] op_sel_hi:[1,0]
	v_pk_mul_f32 v[8:9], v[8:9], v[40:41]
	v_pk_add_f32 v[72:73], v[72:73], 1.0 op_sel_hi:[1,0]
	v_pk_fma_f32 v[8:9], v[8:9], v[72:73], v[56:57]
	v_pk_mul_f32 v[10:11], v[10:11], v[6:7] op_sel_hi:[1,0]
	v_pk_mul_f32 v[10:11], v[10:11], v[42:43]
	v_pk_add_f32 v[74:75], v[74:75], 1.0 op_sel_hi:[1,0]
	v_pk_fma_f32 v[10:11], v[10:11], v[74:75], v[58:59]
	v_bfe_u32 v92, v8, 16, 1
	v_bfe_u32 v93, v9, 16, 1
	v_bfe_u32 v94, v10, 16, 1
	v_bfe_u32 v95, v11, 16, 1
	v_add3_u32 v92, v8, v92, s40
	v_add3_u32 v93, v9, v93, s40
	v_add3_u32 v94, v10, v94, s40
	v_add3_u32 v95, v11, v95, s40
	v_lshrrev_b32_e32 v92, 16, v92
	v_lshrrev_b32_e32 v94, 16, v94
	v_and_or_b32 v96, v93, s41, v92
	v_and_or_b32 v97, v95, s41, v94
	global_store_dwordx2 v2, v[96:97], s[66:67] offset:0
	global_load_dwordx4 v[40:43], v7, s[72:73]
	global_load_dwordx4 v[56:59], v7, s[80:81]
	global_load_dwordx4 v[72:75], v7, s[30:31]
	s_waitcnt vmcnt(10)
	v_pk_mul_f32 v[12:13], v[12:13], v[6:7] op_sel_hi:[1,0]
	v_pk_mul_f32 v[12:13], v[12:13], v[44:45]
	v_pk_add_f32 v[76:77], v[76:77], 1.0 op_sel_hi:[1,0]
	v_pk_fma_f32 v[12:13], v[12:13], v[76:77], v[60:61]
	v_pk_mul_f32 v[14:15], v[14:15], v[6:7] op_sel_hi:[1,0]
	v_pk_mul_f32 v[14:15], v[14:15], v[46:47]
	v_pk_add_f32 v[78:79], v[78:79], 1.0 op_sel_hi:[1,0]
	v_pk_fma_f32 v[14:15], v[14:15], v[78:79], v[62:63]
	v_bfe_u32 v92, v12, 16, 1
	v_bfe_u32 v93, v13, 16, 1
	v_bfe_u32 v94, v14, 16, 1
	v_bfe_u32 v95, v15, 16, 1
	v_add3_u32 v92, v12, v92, s40
	v_add3_u32 v93, v13, v93, s40
	v_add3_u32 v94, v14, v94, s40
	v_add3_u32 v95, v15, v95, s40
	v_lshrrev_b32_e32 v92, 16, v92
	v_lshrrev_b32_e32 v94, 16, v94
	v_and_or_b32 v96, v93, s41, v92
	v_and_or_b32 v97, v95, s41, v94
	global_store_dwordx2 v2, v[96:97], s[66:67] offset:512
	global_load_dwordx4 v[44:47], v7, s[72:73] offset:1024
	global_load_dwordx4 v[60:63], v7, s[80:81] offset:1024
	global_load_dwordx4 v[76:79], v7, s[30:31] offset:1024
	s_waitcnt vmcnt(11)
	v_pk_mul_f32 v[16:17], v[16:17], v[6:7] op_sel_hi:[1,0]
	v_pk_mul_f32 v[16:17], v[16:17], v[48:49]
	v_pk_add_f32 v[80:81], v[80:81], 1.0 op_sel_hi:[1,0]
	v_pk_fma_f32 v[16:17], v[16:17], v[80:81], v[64:65]
	v_pk_mul_f32 v[18:19], v[18:19], v[6:7] op_sel_hi:[1,0]
	v_pk_mul_f32 v[18:19], v[18:19], v[50:51]
	v_pk_add_f32 v[82:83], v[82:83], 1.0 op_sel_hi:[1,0]
	v_pk_fma_f32 v[18:19], v[18:19], v[82:83], v[66:67]
	v_bfe_u32 v92, v16, 16, 1
	v_bfe_u32 v93, v17, 16, 1
	v_bfe_u32 v94, v18, 16, 1
	v_bfe_u32 v95, v19, 16, 1
	v_add3_u32 v92, v16, v92, s40
	v_add3_u32 v93, v17, v93, s40
	v_add3_u32 v94, v18, v94, s40
	v_add3_u32 v95, v19, v95, s40
	v_lshrrev_b32_e32 v92, 16, v92
	v_lshrrev_b32_e32 v94, 16, v94
	v_and_or_b32 v96, v93, s41, v92
	v_and_or_b32 v97, v95, s41, v94
	global_store_dwordx2 v2, v[96:97], s[66:67] offset:1024
	global_load_dwordx4 v[48:51], v7, s[72:73] offset:2048
	global_load_dwordx4 v[64:67], v7, s[80:81] offset:2048
	global_load_dwordx4 v[80:83], v7, s[30:31] offset:2048
	s_waitcnt vmcnt(12)
	v_pk_mul_f32 v[20:21], v[20:21], v[6:7] op_sel_hi:[1,0]
	v_pk_mul_f32 v[20:21], v[20:21], v[52:53]
	v_pk_add_f32 v[88:89], v[88:89], 1.0 op_sel_hi:[1,0]
	v_pk_fma_f32 v[20:21], v[20:21], v[88:89], v[68:69]
	v_pk_mul_f32 v[22:23], v[22:23], v[6:7] op_sel_hi:[1,0]
	v_pk_mul_f32 v[22:23], v[22:23], v[54:55]
	v_pk_add_f32 v[90:91], v[90:91], 1.0 op_sel_hi:[1,0]
	v_pk_fma_f32 v[22:23], v[22:23], v[90:91], v[70:71]
	v_bfe_u32 v92, v20, 16, 1
	v_bfe_u32 v93, v21, 16, 1
	v_bfe_u32 v94, v22, 16, 1
	v_bfe_u32 v95, v23, 16, 1
	v_add3_u32 v92, v20, v92, s40
	v_add3_u32 v93, v21, v93, s40
	v_add3_u32 v94, v22, v94, s40
	v_add3_u32 v95, v23, v95, s40
	v_lshrrev_b32_e32 v92, 16, v92
	v_lshrrev_b32_e32 v94, 16, v94
	v_and_or_b32 v96, v93, s41, v92
	v_and_or_b32 v97, v95, s41, v94
	global_store_dwordx2 v2, v[96:97], s[66:67] offset:1536
	global_load_dwordx4 v[52:55], v7, s[72:73] offset:3072
	global_load_dwordx4 v[68:71], v7, s[80:81] offset:3072
	global_load_dwordx4 v[88:91], v7, s[30:31] offset:3072
	s_waitcnt vmcnt(12)
	v_pk_mul_f32 v[24:25], v[24:25], v[6:7] op_sel_hi:[1,0]
	v_pk_mul_f32 v[24:25], v[24:25], v[40:41]
	v_pk_add_f32 v[72:73], v[72:73], 1.0 op_sel_hi:[1,0]
	v_pk_fma_f32 v[24:25], v[24:25], v[72:73], v[56:57]
	v_pk_mul_f32 v[26:27], v[26:27], v[6:7] op_sel_hi:[1,0]
	v_pk_mul_f32 v[26:27], v[26:27], v[42:43]
	v_pk_add_f32 v[74:75], v[74:75], 1.0 op_sel_hi:[1,0]
	v_pk_fma_f32 v[26:27], v[26:27], v[74:75], v[58:59]
	v_bfe_u32 v92, v24, 16, 1
	v_bfe_u32 v93, v25, 16, 1
	v_bfe_u32 v94, v26, 16, 1
	v_bfe_u32 v95, v27, 16, 1
	v_add3_u32 v92, v24, v92, s40
	v_add3_u32 v93, v25, v93, s40
	v_add3_u32 v94, v26, v94, s40
	v_add3_u32 v95, v27, v95, s40
	v_lshrrev_b32_e32 v92, 16, v92
	v_lshrrev_b32_e32 v94, 16, v94
	v_and_or_b32 v96, v93, s41, v92
	v_and_or_b32 v97, v95, s41, v94
	global_store_dwordx2 v2, v[96:97], s[66:67] offset:2048
	s_waitcnt vmcnt(9)
	v_pk_mul_f32 v[28:29], v[28:29], v[6:7] op_sel_hi:[1,0]
	v_pk_mul_f32 v[28:29], v[28:29], v[44:45]
	v_pk_add_f32 v[76:77], v[76:77], 1.0 op_sel_hi:[1,0]
	v_pk_fma_f32 v[28:29], v[28:29], v[76:77], v[60:61]
	v_pk_mul_f32 v[30:31], v[30:31], v[6:7] op_sel_hi:[1,0]
	v_pk_mul_f32 v[30:31], v[30:31], v[46:47]
	v_pk_add_f32 v[78:79], v[78:79], 1.0 op_sel_hi:[1,0]
	v_pk_fma_f32 v[30:31], v[30:31], v[78:79], v[62:63]
	v_bfe_u32 v92, v28, 16, 1
	v_bfe_u32 v93, v29, 16, 1
	v_bfe_u32 v94, v30, 16, 1
	v_bfe_u32 v95, v31, 16, 1
	v_add3_u32 v92, v28, v92, s40
	v_add3_u32 v93, v29, v93, s40
	v_add3_u32 v94, v30, v94, s40
	v_add3_u32 v95, v31, v95, s40
	v_lshrrev_b32_e32 v92, 16, v92
	v_lshrrev_b32_e32 v94, 16, v94
	v_and_or_b32 v96, v93, s41, v92
	v_and_or_b32 v97, v95, s41, v94
	global_store_dwordx2 v2, v[96:97], s[66:67] offset:2560
	s_waitcnt vmcnt(6)
	v_pk_mul_f32 v[32:33], v[32:33], v[6:7] op_sel_hi:[1,0]
	v_pk_mul_f32 v[32:33], v[32:33], v[48:49]
	v_pk_add_f32 v[80:81], v[80:81], 1.0 op_sel_hi:[1,0]
	v_pk_fma_f32 v[32:33], v[32:33], v[80:81], v[64:65]
	v_pk_mul_f32 v[34:35], v[34:35], v[6:7] op_sel_hi:[1,0]
	v_pk_mul_f32 v[34:35], v[34:35], v[50:51]
	v_pk_add_f32 v[82:83], v[82:83], 1.0 op_sel_hi:[1,0]
	v_pk_fma_f32 v[34:35], v[34:35], v[82:83], v[66:67]
	v_bfe_u32 v92, v32, 16, 1
	v_bfe_u32 v93, v33, 16, 1
	v_bfe_u32 v94, v34, 16, 1
	v_bfe_u32 v95, v35, 16, 1
	v_add3_u32 v92, v32, v92, s40
	v_add3_u32 v93, v33, v93, s40
	v_add3_u32 v94, v34, v94, s40
	v_add3_u32 v95, v35, v95, s40
	v_lshrrev_b32_e32 v92, 16, v92
	v_lshrrev_b32_e32 v94, 16, v94
	v_and_or_b32 v96, v93, s41, v92
	v_and_or_b32 v97, v95, s41, v94
	global_store_dwordx2 v2, v[96:97], s[66:67] offset:3072
	s_waitcnt vmcnt(3)
	v_pk_mul_f32 v[36:37], v[36:37], v[6:7] op_sel_hi:[1,0]
	v_pk_mul_f32 v[36:37], v[36:37], v[52:53]
	v_pk_add_f32 v[88:89], v[88:89], 1.0 op_sel_hi:[1,0]
	v_pk_fma_f32 v[36:37], v[36:37], v[88:89], v[68:69]
	v_pk_mul_f32 v[38:39], v[38:39], v[6:7] op_sel_hi:[1,0]
	v_pk_mul_f32 v[38:39], v[38:39], v[54:55]
	v_pk_add_f32 v[90:91], v[90:91], 1.0 op_sel_hi:[1,0]
	v_pk_fma_f32 v[38:39], v[38:39], v[90:91], v[70:71]
	v_bfe_u32 v92, v36, 16, 1
	v_bfe_u32 v93, v37, 16, 1
	v_bfe_u32 v94, v38, 16, 1
	v_bfe_u32 v95, v39, 16, 1
	v_add3_u32 v92, v36, v92, s40
	v_add3_u32 v93, v37, v93, s40
	v_add3_u32 v94, v38, v94, s40
	v_add3_u32 v95, v39, v95, s40
	v_lshrrev_b32_e32 v92, 16, v92
	v_lshrrev_b32_e32 v94, 16, v94
	v_and_or_b32 v96, v93, s41, v92
	v_and_or_b32 v97, v95, s41, v94
	global_store_dwordx2 v2, v[96:97], s[66:67] offset:3584
	s_add_u32 s54, s54, s55
	s_cmp_lt_u32 s54, 0x3000
	s_cbranch_scc1 .Lnr1_row
.Lnr1_done:
	s_mov_b64 s[50:51], exec

.LBB0_1212:
	s_or_b64 exec, exec, s[4:5]
	s_waitcnt lgkmcnt(0)
	s_barrier
	s_mov_b32 s6, 0
	v_mov_b32 v0, v148
	v_readlane_b32 s4, v253, 8
	v_lshrrev_b32_e32 v1, 6, v0
	s_waitcnt vmcnt(35)
	v_or_b32_e32 v32, s4, v1
	v_cmp_gt_i32_e32 vcc, s33, v32
	s_and_saveexec_b64 s[4:5], vcc
	s_cbranch_execz .LBB0_1231
	v_readlane_b32 s6, v253, 8
	v_lshrrev_b32_e32 v1, 6, v148
	v_readlane_b32 s7, v253, 1
	v_readfirstlane_b32 s38, v1
	v_readlane_b32 s30, v253, 3
	v_readlane_b32 s31, v253, 4
	s_add_u32 s6, s6, s38
	s_lshl_b32 s7, s7, 3
	s_load_dwordx2 s[70:71], s[30:31], 0x100
	s_load_dwordx2 s[72:73], s[30:31], 0x58
	v_readlane_b32 s38, v252, 11
	v_readlane_b32 s44, v252, 13
	v_readlane_b32 s45, v252, 14
	v_and_b32_e32 v0, 63, v148
	v_lshlrev_b32_e32 v1, 4, v0
	v_lshlrev_b32_e32 v2, 3, v0
	v_and_b32_e32 v3, 7, v0
	v_lshlrev_b32_e32 v3, 2, v3
	v_add_u32_e32 v7, 0x1000, v1
	s_lshl_b32 s38, s38, 13
	s_lshl_b64 s[44:45], s[44:45], 2
	s_waitcnt lgkmcnt(0)
	s_add_u32 s72, s72, s38
	s_addc_u32 s73, s73, 0
	s_add_u32 s44, s44, s70
	s_addc_u32 s45, s45, s71
	s_add_u32 s44, s44, 0x28b06000
	s_addc_u32 s45, s45, 0
	s_add_u32 s74, s70, 0x2fc80100
	s_addc_u32 s75, s71, 0
	s_add_u32 s76, s70, 0xc000000
	s_addc_u32 s77, s71, 0
	s_add_u32 s78, s70, 0x21000000
	s_addc_u32 s79, s71, 0
	s_cmp_lt_u32 s6, 0x3000
	s_cbranch_scc0 .Lnr2_done
.Lnr2_row:
	s_lshl_b32 s38, s6, 13
	s_add_u32 s64, s76, s38
	s_addc_u32 s65, s77, 0
	s_lshr_b32 s39, s6, 8
	s_lshl_b32 s39, s39, 5
	s_add_u32 s38, s74, s39
	s_addc_u32 s39, s75, 0
	global_load_dword v4, v3, s[38:39]
	global_load_dwordx4 v[8:11], v1, s[64:65]
	global_load_dwordx4 v[12:15], v1, s[64:65] offset:1024
	global_load_dwordx4 v[16:19], v1, s[64:65] offset:2048
	global_load_dwordx4 v[20:23], v1, s[64:65] offset:3072
	global_load_dwordx4 v[24:27], v7, s[64:65]
	global_load_dwordx4 v[28:31], v7, s[64:65] offset:1024
	global_load_dwordx4 v[32:35], v7, s[64:65] offset:2048
	global_load_dwordx4 v[36:39], v7, s[64:65] offset:3072
	s_waitcnt vmcnt(8)
	v_readlane_b32 s56, v4, 0
	v_readlane_b32 s57, v4, 1
	v_readlane_b32 s58, v4, 2
	v_readlane_b32 s59, v4, 3
	v_readlane_b32 s60, v4, 4
	v_readlane_b32 s61, v4, 5
	v_readlane_b32 s62, v4, 6
	v_readlane_b32 s63, v4, 7
	s_and_b32 s38, s6, 0xff
	s_cmp_lt_i32 s56, 0
	s_cbranch_scc1 .Lnr2_sl0
	s_lshl_b32 s39, s56, 8
	s_add_u32 s39, s39, s38
	s_lshl_b32 s39, s39, 10
	s_add_u32 s30, s78, s39
	s_addc_u32 s31, s79, 0
	global_load_dwordx4 v[40:43], v1, s[30:31]
.Lnr2_sl0:
	s_cmp_lt_i32 s57, 0
	s_cbranch_scc1 .Lnr2_sl1
	s_lshl_b32 s39, s57, 8
	s_add_u32 s39, s39, s38
	s_lshl_b32 s39, s39, 10
	s_add_u32 s30, s78, s39
	s_addc_u32 s31, s79, 0
	global_load_dwordx4 v[44:47], v1, s[30:31]
.Lnr2_sl1:
	s_cmp_lt_i32 s58, 0
	s_cbranch_scc1 .Lnr2_sl2
	s_lshl_b32 s39, s58, 8
	s_add_u32 s39, s39, s38
	s_lshl_b32 s39, s39, 10
	s_add_u32 s30, s78, s39
	s_addc_u32 s31, s79, 0
	global_load_dwordx4 v[48:51], v1, s[30:31]
.Lnr2_sl2:
	s_cmp_lt_i32 s59, 0
	s_cbranch_scc1 .Lnr2_sl3
	s_lshl_b32 s39, s59, 8
	s_add_u32 s39, s39, s38
	s_lshl_b32 s39, s39, 10
	s_add_u32 s30, s78, s39
	s_addc_u32 s31, s79, 0
	global_load_dwordx4 v[52:55], v1, s[30:31]
.Lnr2_sl3:
	s_cmp_lt_i32 s60, 0
	s_cbranch_scc1 .Lnr2_sl4
	s_lshl_b32 s39, s60, 8
	s_add_u32 s39, s39, s38
	s_lshl_b32 s39, s39, 10
	s_add_u32 s30, s78, s39
	s_addc_u32 s31, s79, 0
	global_load_dwordx4 v[56:59], v1, s[30:31]
.Lnr2_sl4:
	s_cmp_lt_i32 s61, 0
	s_cbranch_scc1 .Lnr2_sl5
	s_lshl_b32 s39, s61, 8
	s_add_u32 s39, s39, s38
	s_lshl_b32 s39, s39, 10
	s_add_u32 s30, s78, s39
	s_addc_u32 s31, s79, 0
	global_load_dwordx4 v[60:63], v1, s[30:31]
.Lnr2_sl5:
	s_cmp_lt_i32 s62, 0
	s_cbranch_scc1 .Lnr2_sl6
	s_lshl_b32 s39, s62, 8
	s_add_u32 s39, s39, s38
	s_lshl_b32 s39, s39, 10
	s_add_u32 s30, s78, s39
	s_addc_u32 s31, s79, 0
	global_load_dwordx4 v[64:67], v1, s[30:31]
.Lnr2_sl6:
	s_cmp_lt_i32 s63, 0
	s_cbranch_scc1 .Lnr2_sl7
	s_lshl_b32 s39, s63, 8
	s_add_u32 s39, s39, s38
	s_lshl_b32 s39, s39, 10
	s_add_u32 s30, s78, s39
	s_addc_u32 s31, s79, 0
	global_load_dwordx4 v[68:71], v1, s[30:31]

.Lnr2_sa7:
	s_sub_u32 s39, s6, 0x1000
	s_lshr_b32 s39, s39, 11
	s_add_u32 s39, s39, 1
	s_mul_i32 s39, s39, 0xc000
	s_cmp_lt_u32 s6, 0x1000
	s_cselect_b32 s38, 0, s39
	s_add_u32 s80, s44, s38
	s_addc_u32 s81, s45, 0
	s_add_u32 s30, s80, 0x2000
	s_addc_u32 s31, s81, 0
	global_load_dwordx4 v[40:43], v1, s[72:73]
	global_load_dwordx4 v[56:59], v1, s[80:81]
	global_load_dwordx4 v[72:75], v1, s[30:31]
	global_load_dwordx4 v[44:47], v1, s[72:73] offset:1024
	global_load_dwordx4 v[60:63], v1, s[80:81] offset:1024
	global_load_dwordx4 v[76:79], v1, s[30:31] offset:1024
	global_load_dwordx4 v[48:51], v1, s[72:73] offset:2048
	global_load_dwordx4 v[64:67], v1, s[80:81] offset:2048
	global_load_dwordx4 v[80:83], v1, s[30:31] offset:2048
	global_load_dwordx4 v[52:55], v1, s[72:73] offset:3072
	global_load_dwordx4 v[68:71], v1, s[80:81] offset:3072
	global_load_dwordx4 v[88:91], v1, s[30:31] offset:3072
	s_lshl_b32 s38, s6, 12
	s_add_u32 s66, s70, 0x12000000
	s_addc_u32 s67, s71, 0
	s_add_u32 s66, s66, s38
	s_addc_u32 s67, s67, 0
	v_pk_mul_f32 v[92:93], v[8:9], v[8:9]
	v_pk_fma_f32 v[92:93], v[10:11], v[10:11], v[92:93]
	v_pk_fma_f32 v[92:93], v[12:13], v[12:13], v[92:93]
	v_pk_fma_f32 v[92:93], v[14:15], v[14:15], v[92:93]
	v_pk_fma_f32 v[92:93], v[16:17], v[16:17], v[92:93]
	v_pk_fma_f32 v[92:93], v[18:19], v[18:19], v[92:93]
	v_pk_fma_f32 v[92:93], v[20:21], v[20:21], v[92:93]
	v_pk_fma_f32 v[92:93], v[22:23], v[22:23], v[92:93]
	v_pk_fma_f32 v[92:93], v[24:25], v[24:25], v[92:93]
	v_pk_fma_f32 v[92:93], v[26:27], v[26:27], v[92:93]
	v_pk_fma_f32 v[92:93], v[28:29], v[28:29], v[92:93]
	v_pk_fma_f32 v[92:93], v[30:31], v[30:31], v[92:93]
	v_pk_fma_f32 v[92:93], v[32:33], v[32:33], v[92:93]
	v_pk_fma_f32 v[92:93], v[34:35], v[34:35], v[92:93]
	v_pk_fma_f32 v[92:93], v[36:37], v[36:37], v[92:93]
	v_pk_fma_f32 v[92:93], v[38:39], v[38:39], v[92:93]
	v_add_f32_e32 v5, v92, v93
	s_nop 1
	v_add_f32_dpp v5, v5, v5 quad_perm:[1,0,3,2] row_mask:0xf bank_mask:0xf bound_ctrl:1
	s_nop 1
	v_add_f32_dpp v5, v5, v5 quad_perm:[2,3,0,1] row_mask:0xf bank_mask:0xf bound_ctrl:1
	s_nop 1
	v_add_f32_dpp v5, v5, v5 row_half_mirror row_mask:0xf bank_mask:0xf bound_ctrl:1
	s_nop 1
	v_add_f32_dpp v5, v5, v5 row_mirror row_mask:0xf bank_mask:0xf bound_ctrl:1
	s_nop 1
	v_readlane_b32 s38, v5, 0
	v_readlane_b32 s39, v5, 16
	v_readlane_b32 s56, v5, 32
	v_readlane_b32 s57, v5, 48
	s_nop 1
	v_mov_b32_e32 v5, s38
	v_add_f32_e32 v5, s39, v5
	v_add_f32_e32 v5, s56, v5
	v_add_f32_e32 v5, s57, v5
	v_mov_b32_e32 v6, 0x358637bd
	v_fmamk_f32 v5, v5, 0x3a000000, v6
	v_rsq_f32_e32 v6, v5
	s_movk_i32 s38, 0x7fff
	s_mov_b32 s39, 0xffff0000
	s_waitcnt vmcnt(9)
	v_pk_mul_f32 v[8:9], v[8:9], v[6:7] op_sel_hi:[1,0]
	v_pk_mul_f32 v[8:9], v[8:9], v[40:41]
	v_pk_add_f32 v[72:73], v[72:73], 1.0 op_sel_hi:[1,0]
	v_pk_fma_f32 v[8:9], v[8:9], v[72:73], v[56:57]
	v_pk_mul_f32 v[10:11], v[10:11], v[6:7] op_sel_hi:[1,0]
	v_pk_mul_f32 v[10:11], v[10:11], v[42:43]
	v_pk_add_f32 v[74:75], v[74:75], 1.0 op_sel_hi:[1,0]
	v_pk_fma_f32 v[10:11], v[10:11], v[74:75], v[58:59]
	v_bfe_u32 v92, v8, 16, 1
	v_bfe_u32 v93, v9, 16, 1
	v_bfe_u32 v94, v10, 16, 1
	v_bfe_u32 v95, v11, 16, 1
	v_add3_u32 v92, v8, v92, s38
	v_add3_u32 v93, v9, v93, s38
	v_add3_u32 v94, v10, v94, s38
	v_add3_u32 v95, v11, v95, s38
	v_lshrrev_b32_e32 v92, 16, v92
	v_lshrrev_b32_e32 v94, 16, v94
	v_and_or_b32 v96, v93, s39, v92
	v_and_or_b32 v97, v95, s39, v94
	global_store_dwordx2 v2, v[96:97], s[66:67] offset:0
	global_load_dwordx4 v[40:43], v7, s[72:73]
	global_load_dwordx4 v[56:59], v7, s[80:81]
	global_load_dwordx4 v[72:75], v7, s[30:31]
	s_waitcnt vmcnt(10)
	v_pk_mul_f32 v[12:13], v[12:13], v[6:7] op_sel_hi:[1,0]
	v_pk_mul_f32 v[12:13], v[12:13], v[44:45]
	v_pk_add_f32 v[76:77], v[76:77], 1.0 op_sel_hi:[1,0]
	v_pk_fma_f32 v[12:13], v[12:13], v[76:77], v[60:61]
	v_pk_mul_f32 v[14:15], v[14:15], v[6:7] op_sel_hi:[1,0]
	v_pk_mul_f32 v[14:15], v[14:15], v[46:47]
	v_pk_add_f32 v[78:79], v[78:79], 1.0 op_sel_hi:[1,0]
	v_pk_fma_f32 v[14:15], v[14:15], v[78:79], v[62:63]
	v_bfe_u32 v92, v12, 16, 1
	v_bfe_u32 v93, v13, 16, 1
	v_bfe_u32 v94, v14, 16, 1
	v_bfe_u32 v95, v15, 16, 1
	v_add3_u32 v92, v12, v92, s38
	v_add3_u32 v93, v13, v93, s38
	v_add3_u32 v94, v14, v94, s38
	v_add3_u32 v95, v15, v95, s38
	v_lshrrev_b32_e32 v92, 16, v92
	v_lshrrev_b32_e32 v94, 16, v94
	v_and_or_b32 v96, v93, s39, v92
	v_and_or_b32 v97, v95, s39, v94
	global_store_dwordx2 v2, v[96:97], s[66:67] offset:512
	global_load_dwordx4 v[44:47], v7, s[72:73] offset:1024
	global_load_dwordx4 v[60:63], v7, s[80:81] offset:1024
	global_load_dwordx4 v[76:79], v7, s[30:31] offset:1024
	s_waitcnt vmcnt(11)
	v_pk_mul_f32 v[16:17], v[16:17], v[6:7] op_sel_hi:[1,0]
	v_pk_mul_f32 v[16:17], v[16:17], v[48:49]
	v_pk_add_f32 v[80:81], v[80:81], 1.0 op_sel_hi:[1,0]
	v_pk_fma_f32 v[16:17], v[16:17], v[80:81], v[64:65]
	v_pk_mul_f32 v[18:19], v[18:19], v[6:7] op_sel_hi:[1,0]
	v_pk_mul_f32 v[18:19], v[18:19], v[50:51]
	v_pk_add_f32 v[82:83], v[82:83], 1.0 op_sel_hi:[1,0]
	v_pk_fma_f32 v[18:19], v[18:19], v[82:83], v[66:67]
	v_bfe_u32 v92, v16, 16, 1
	v_bfe_u32 v93, v17, 16, 1
	v_bfe_u32 v94, v18, 16, 1
	v_bfe_u32 v95, v19, 16, 1
	v_add3_u32 v92, v16, v92, s38
	v_add3_u32 v93, v17, v93, s38
	v_add3_u32 v94, v18, v94, s38
	v_add3_u32 v95, v19, v95, s38
	v_lshrrev_b32_e32 v92, 16, v92
	v_lshrrev_b32_e32 v94, 16, v94
	v_and_or_b32 v96, v93, s39, v92
	v_and_or_b32 v97, v95, s39, v94
	global_store_dwordx2 v2, v[96:97], s[66:67] offset:1024
	global_load_dwordx4 v[48:51], v7, s[72:73] offset:2048
	global_load_dwordx4 v[64:67], v7, s[80:81] offset:2048
	global_load_dwordx4 v[80:83], v7, s[30:31] offset:2048
	s_waitcnt vmcnt(12)
	v_pk_mul_f32 v[20:21], v[20:21], v[6:7] op_sel_hi:[1,0]
	v_pk_mul_f32 v[20:21], v[20:21], v[52:53]
	v_pk_add_f32 v[88:89], v[88:89], 1.0 op_sel_hi:[1,0]
	v_pk_fma_f32 v[20:21], v[20:21], v[88:89], v[68:69]
	v_pk_mul_f32 v[22:23], v[22:23], v[6:7] op_sel_hi:[1,0]
	v_pk_mul_f32 v[22:23], v[22:23], v[54:55]
	v_pk_add_f32 v[90:91], v[90:91], 1.0 op_sel_hi:[1,0]
	v_pk_fma_f32 v[22:23], v[22:23], v[90:91], v[70:71]
	v_bfe_u32 v92, v20, 16, 1
	v_bfe_u32 v93, v21, 16, 1
	v_bfe_u32 v94, v22, 16, 1
	v_bfe_u32 v95, v23, 16, 1
	v_add3_u32 v92, v20, v92, s38
	v_add3_u32 v93, v21, v93, s38
	v_add3_u32 v94, v22, v94, s38
	v_add3_u32 v95, v23, v95, s38
	v_lshrrev_b32_e32 v92, 16, v92
	v_lshrrev_b32_e32 v94, 16, v94
	v_and_or_b32 v96, v93, s39, v92
	v_and_or_b32 v97, v95, s39, v94
	global_store_dwordx2 v2, v[96:97], s[66:67] offset:1536
	global_load_dwordx4 v[52:55], v7, s[72:73] offset:3072
	global_load_dwordx4 v[68:71], v7, s[80:81] offset:3072
	global_load_dwordx4 v[88:91], v7, s[30:31] offset:3072
	s_waitcnt vmcnt(12)
	v_pk_mul_f32 v[24:25], v[24:25], v[6:7] op_sel_hi:[1,0]
	v_pk_mul_f32 v[24:25], v[24:25], v[40:41]
	v_pk_add_f32 v[72:73], v[72:73], 1.0 op_sel_hi:[1,0]
	v_pk_fma_f32 v[24:25], v[24:25], v[72:73], v[56:57]
	v_pk_mul_f32 v[26:27], v[26:27], v[6:7] op_sel_hi:[1,0]
	v_pk_mul_f32 v[26:27], v[26:27], v[42:43]
	v_pk_add_f32 v[74:75], v[74:75], 1.0 op_sel_hi:[1,0]
	v_pk_fma_f32 v[26:27], v[26:27], v[74:75], v[58:59]
	v_bfe_u32 v92, v24, 16, 1
	v_bfe_u32 v93, v25, 16, 1
	v_bfe_u32 v94, v26, 16, 1
	v_bfe_u32 v95, v27, 16, 1
	v_add3_u32 v92, v24, v92, s38
	v_add3_u32 v93, v25, v93, s38
	v_add3_u32 v94, v26, v94, s38
	v_add3_u32 v95, v27, v95, s38
	v_lshrrev_b32_e32 v92, 16, v92
	v_lshrrev_b32_e32 v94, 16, v94
	v_and_or_b32 v96, v93, s39, v92
	v_and_or_b32 v97, v95, s39, v94
	global_store_dwordx2 v2, v[96:97], s[66:67] offset:2048
	s_waitcnt vmcnt(9)
	v_pk_mul_f32 v[28:29], v[28:29], v[6:7] op_sel_hi:[1,0]
	v_pk_mul_f32 v[28:29], v[28:29], v[44:45]
	v_pk_add_f32 v[76:77], v[76:77], 1.0 op_sel_hi:[1,0]
	v_pk_fma_f32 v[28:29], v[28:29], v[76:77], v[60:61]
	v_pk_mul_f32 v[30:31], v[30:31], v[6:7] op_sel_hi:[1,0]
	v_pk_mul_f32 v[30:31], v[30:31], v[46:47]
	v_pk_add_f32 v[78:79], v[78:79], 1.0 op_sel_hi:[1,0]
	v_pk_fma_f32 v[30:31], v[30:31], v[78:79], v[62:63]
	v_bfe_u32 v92, v28, 16, 1
	v_bfe_u32 v93, v29, 16, 1
	v_bfe_u32 v94, v30, 16, 1
	v_bfe_u32 v95, v31, 16, 1
	v_add3_u32 v92, v28, v92, s38
	v_add3_u32 v93, v29, v93, s38
	v_add3_u32 v94, v30, v94, s38
	v_add3_u32 v95, v31, v95, s38
	v_lshrrev_b32_e32 v92, 16, v92
	v_lshrrev_b32_e32 v94, 16, v94
	v_and_or_b32 v96, v93, s39, v92
	v_and_or_b32 v97, v95, s39, v94
	global_store_dwordx2 v2, v[96:97], s[66:67] offset:2560
	s_waitcnt vmcnt(6)
	v_pk_mul_f32 v[32:33], v[32:33], v[6:7] op_sel_hi:[1,0]
	v_pk_mul_f32 v[32:33], v[32:33], v[48:49]
	v_pk_add_f32 v[80:81], v[80:81], 1.0 op_sel_hi:[1,0]
	v_pk_fma_f32 v[32:33], v[32:33], v[80:81], v[64:65]
	v_pk_mul_f32 v[34:35], v[34:35], v[6:7] op_sel_hi:[1,0]
	v_pk_mul_f32 v[34:35], v[34:35], v[50:51]
	v_pk_add_f32 v[82:83], v[82:83], 1.0 op_sel_hi:[1,0]
	v_pk_fma_f32 v[34:35], v[34:35], v[82:83], v[66:67]
	v_bfe_u32 v92, v32, 16, 1
	v_bfe_u32 v93, v33, 16, 1
	v_bfe_u32 v94, v34, 16, 1
	v_bfe_u32 v95, v35, 16, 1
	v_add3_u32 v92, v32, v92, s38
	v_add3_u32 v93, v33, v93, s38
	v_add3_u32 v94, v34, v94, s38
	v_add3_u32 v95, v35, v95, s38
	v_lshrrev_b32_e32 v92, 16, v92
	v_lshrrev_b32_e32 v94, 16, v94
	v_and_or_b32 v96, v93, s39, v92
	v_and_or_b32 v97, v95, s39, v94
	global_store_dwordx2 v2, v[96:97], s[66:67] offset:3072
	s_waitcnt vmcnt(3)
	v_pk_mul_f32 v[36:37], v[36:37], v[6:7] op_sel_hi:[1,0]
	v_pk_mul_f32 v[36:37], v[36:37], v[52:53]
	v_pk_add_f32 v[88:89], v[88:89], 1.0 op_sel_hi:[1,0]
	v_pk_fma_f32 v[36:37], v[36:37], v[88:89], v[68:69]
	v_pk_mul_f32 v[38:39], v[38:39], v[6:7] op_sel_hi:[1,0]
	v_pk_mul_f32 v[38:39], v[38:39], v[54:55]
	v_pk_add_f32 v[90:91], v[90:91], 1.0 op_sel_hi:[1,0]
	v_pk_fma_f32 v[38:39], v[38:39], v[90:91], v[70:71]
	v_bfe_u32 v92, v36, 16, 1
	v_bfe_u32 v93, v37, 16, 1
	v_bfe_u32 v94, v38, 16, 1
	v_bfe_u32 v95, v39, 16, 1
	v_add3_u32 v92, v36, v92, s38
	v_add3_u32 v93, v37, v93, s38
	v_add3_u32 v94, v38, v94, s38
	v_add3_u32 v95, v39, v95, s38
	v_lshrrev_b32_e32 v92, 16, v92
	v_lshrrev_b32_e32 v94, 16, v94
	v_and_or_b32 v96, v93, s39, v92
	v_and_or_b32 v97, v95, s39, v94
	global_store_dwordx2 v2, v[96:97], s[66:67] offset:3584
	s_add_u32 s6, s6, s7
	s_cmp_lt_u32 s6, 0x3000
	s_cbranch_scc1 .Lnr2_row
.Lnr2_done:
.LBB0_1231:
	s_or_b64 exec, exec, s[4:5]
	s_waitcnt vmcnt(0)
	s_barrier
	s_mov_b64 s[4:5], exec
	v_readlane_b32 s6, v253, 6
	v_readlane_b32 s7, v253, 7
	s_and_b64 s[6:7], s[4:5], s[6:7]
	s_mov_b64 exec, s[6:7]
	s_cbranch_execz .LBB0_1283
	v_readlane_b32 s6, v254, 49
	s_waitcnt vmcnt(0) expcnt(0) lgkmcnt(0)
	s_nop 0
	v_mov_b32_e32 v0, s6
	ds_read_b32 v2, v0
	v_readlane_b32 s6, v254, 50
	s_waitcnt lgkmcnt(0)
	v_cmp_ne_u32_e32 vcc, 0, v2
	v_mov_b32_e32 v0, s6
	ds_read_b32 v0, v0
	s_cbranch_vccnz .LBB0_1247
	s_mov_b32 s6, 1
	s_branch .LBB0_1235

.LBB0_1455:
	v_readlane_b32 s54, v253, 8
	v_lshrrev_b32_e32 v1, 6, v148
	v_readlane_b32 s55, v253, 1
	v_readfirstlane_b32 s40, v1
	v_readlane_b32 s82, v253, 3
	v_readlane_b32 s83, v253, 4
	s_add_u32 s54, s54, s40
	s_lshl_b32 s55, s55, 3
	s_load_dwordx2 s[70:71], s[82:83], 0x100
	s_load_dwordx4 s[72:75], s[82:83], 0xf0
	v_and_b32_e32 v0, 63, v148
	v_lshlrev_b32_e32 v1, 4, v0
	v_and_b32_e32 v3, 7, v0
	v_lshlrev_b32_e32 v3, 2, v3
	v_add_u32_e32 v7, 0x1000, v1
	s_waitcnt lgkmcnt(0)
	s_add_u32 s42, s70, 0xc000000
	s_addc_u32 s43, s71, 0
	s_add_u32 s46, s70, 0x2fc80100
	s_addc_u32 s47, s71, 0
	s_add_u32 s78, s70, 0x21000000
	s_addc_u32 s79, s71, 0
	s_cmp_lt_u32 s54, 0x3000
	s_cbranch_scc0 .Lnf_done
.Lnf_row:
	s_lshl_b32 s40, s54, 13
	s_add_u32 s64, s42, s40
	s_addc_u32 s65, s43, 0
	s_add_u32 s66, s74, s40
	s_addc_u32 s67, s75, 0
	s_lshr_b32 s41, s54, 8
	s_lshl_b32 s41, s41, 5
	s_add_u32 s40, s46, s41
	s_addc_u32 s41, s47, 0
	global_load_dword v4, v3, s[40:41]
	global_load_dwordx4 v[8:11], v1, s[64:65]
	global_load_dwordx4 v[12:15], v1, s[64:65] offset:1024
	global_load_dwordx4 v[16:19], v1, s[64:65] offset:2048
	global_load_dwordx4 v[20:23], v1, s[64:65] offset:3072
	global_load_dwordx4 v[24:27], v7, s[64:65]
	global_load_dwordx4 v[28:31], v7, s[64:65] offset:1024
	global_load_dwordx4 v[32:35], v7, s[64:65] offset:2048
	global_load_dwordx4 v[36:39], v7, s[64:65] offset:3072
	s_waitcnt vmcnt(8)
	v_readlane_b32 s56, v4, 0
	v_readlane_b32 s57, v4, 1
	v_readlane_b32 s58, v4, 2
	v_readlane_b32 s59, v4, 3
	v_readlane_b32 s60, v4, 4
	v_readlane_b32 s61, v4, 5
	v_readlane_b32 s62, v4, 6
	v_readlane_b32 s63, v4, 7
	s_and_b32 s40, s54, 0xff
	s_cmp_lt_i32 s56, 0
	s_cbranch_scc1 .Lnf_sl0
	s_lshl_b32 s41, s56, 8
	s_add_u32 s41, s41, s40
	s_lshl_b32 s41, s41, 10
	s_add_u32 s30, s78, s41
	s_addc_u32 s31, s79, 0
	global_load_dwordx4 v[40:43], v1, s[30:31]

.Lnf_sl7:
	s_waitcnt vmcnt(0)
	s_cmp_lt_i32 s56, 0
	s_cbranch_scc1 .Lnf_sa0
	v_pk_add_f32 v[8:9], v[8:9], v[40:41]
	v_pk_add_f32 v[10:11], v[10:11], v[42:43]
.Lnf_sa0:
	s_cmp_lt_i32 s57, 0
	s_cbranch_scc1 .Lnf_sa1
	v_pk_add_f32 v[12:13], v[12:13], v[44:45]
	v_pk_add_f32 v[14:15], v[14:15], v[46:47]
.Lnf_sa1:
	s_cmp_lt_i32 s58, 0
	s_cbranch_scc1 .Lnf_sa2
	v_pk_add_f32 v[16:17], v[16:17], v[48:49]
	v_pk_add_f32 v[18:19], v[18:19], v[50:51]
.Lnf_sa2:
	s_cmp_lt_i32 s59, 0
	s_cbranch_scc1 .Lnf_sa3
	v_pk_add_f32 v[20:21], v[20:21], v[52:53]
	v_pk_add_f32 v[22:23], v[22:23], v[54:55]
.Lnf_sa3:
	s_cmp_lt_i32 s60, 0
	s_cbranch_scc1 .Lnf_sa4
	v_pk_add_f32 v[24:25], v[24:25], v[56:57]
	v_pk_add_f32 v[26:27], v[26:27], v[58:59]
.Lnf_sa4:
	s_cmp_lt_i32 s61, 0
	s_cbranch_scc1 .Lnf_sa5
	v_pk_add_f32 v[28:29], v[28:29], v[60:61]
	v_pk_add_f32 v[30:31], v[30:31], v[62:63]
.Lnf_sa5:
	s_cmp_lt_i32 s62, 0
	s_cbranch_scc1 .Lnf_sa6
	v_pk_add_f32 v[32:33], v[32:33], v[64:65]
	v_pk_add_f32 v[34:35], v[34:35], v[66:67]
.Lnf_sa6:
	s_cmp_lt_i32 s63, 0
	s_cbranch_scc1 .Lnf_sa7
	v_pk_add_f32 v[36:37], v[36:37], v[68:69]
	v_pk_add_f32 v[38:39], v[38:39], v[70:71]
.Lnf_sa7:
	global_load_dwordx4 v[40:43], v1, s[72:73]
	global_load_dwordx4 v[44:47], v1, s[72:73] offset:1024
	global_load_dwordx4 v[48:51], v1, s[72:73] offset:2048
	global_load_dwordx4 v[52:55], v1, s[72:73] offset:3072
	global_load_dwordx4 v[56:59], v7, s[72:73]
	global_load_dwordx4 v[60:63], v7, s[72:73] offset:1024
	global_load_dwordx4 v[64:67], v7, s[72:73] offset:2048
	global_load_dwordx4 v[68:71], v7, s[72:73] offset:3072
	v_pk_mul_f32 v[92:93], v[8:9], v[8:9]
	v_pk_fma_f32 v[92:93], v[10:11], v[10:11], v[92:93]
	v_pk_fma_f32 v[92:93], v[12:13], v[12:13], v[92:93]
	v_pk_fma_f32 v[92:93], v[14:15], v[14:15], v[92:93]
	v_pk_fma_f32 v[92:93], v[16:17], v[16:17], v[92:93]
	v_pk_fma_f32 v[92:93], v[18:19], v[18:19], v[92:93]
	v_pk_fma_f32 v[92:93], v[20:21], v[20:21], v[92:93]
	v_pk_fma_f32 v[92:93], v[22:23], v[22:23], v[92:93]
	v_pk_fma_f32 v[92:93], v[24:25], v[24:25], v[92:93]
	v_pk_fma_f32 v[92:93], v[26:27], v[26:27], v[92:93]
	v_pk_fma_f32 v[92:93], v[28:29], v[28:29], v[92:93]
	v_pk_fma_f32 v[92:93], v[30:31], v[30:31], v[92:93]
	v_pk_fma_f32 v[92:93], v[32:33], v[32:33], v[92:93]
	v_pk_fma_f32 v[92:93], v[34:35], v[34:35], v[92:93]
	v_pk_fma_f32 v[92:93], v[36:37], v[36:37], v[92:93]
	v_pk_fma_f32 v[92:93], v[38:39], v[38:39], v[92:93]
	v_add_f32_e32 v5, v92, v93
	s_nop 1
	v_add_f32_dpp v5, v5, v5 quad_perm:[1,0,3,2] row_mask:0xf bank_mask:0xf bound_ctrl:1
	s_nop 1
	v_add_f32_dpp v5, v5, v5 quad_perm:[2,3,0,1] row_mask:0xf bank_mask:0xf bound_ctrl:1
	s_nop 1
	v_add_f32_dpp v5, v5, v5 row_half_mirror row_mask:0xf bank_mask:0xf bound_ctrl:1
	s_nop 1
	v_add_f32_dpp v5, v5, v5 row_mirror row_mask:0xf bank_mask:0xf bound_ctrl:1
	s_nop 1
	v_readlane_b32 s40, v5, 0
	v_readlane_b32 s41, v5, 16
	v_readlane_b32 s56, v5, 32
	v_readlane_b32 s57, v5, 48
	s_nop 1
	v_mov_b32_e32 v5, s40
	v_add_f32_e32 v5, s41, v5
	v_add_f32_e32 v5, s56, v5
	v_add_f32_e32 v5, s57, v5
	v_mov_b32_e32 v6, 0x358637bd
	v_fmamk_f32 v5, v5, 0x3a000000, v6
	v_rsq_f32_e32 v6, v5
	s_nop 0
	s_waitcnt vmcnt(7)
	v_pk_mul_f32 v[8:9], v[8:9], v[6:7] op_sel_hi:[1,0]
	v_pk_mul_f32 v[8:9], v[8:9], v[40:41]
	v_pk_mul_f32 v[10:11], v[10:11], v[6:7] op_sel_hi:[1,0]
	v_pk_mul_f32 v[10:11], v[10:11], v[42:43]
	global_store_dwordx4 v1, v[8:11], s[66:67] nt
	s_waitcnt vmcnt(7)
	v_pk_mul_f32 v[12:13], v[12:13], v[6:7] op_sel_hi:[1,0]
	v_pk_mul_f32 v[12:13], v[12:13], v[44:45]
	v_pk_mul_f32 v[14:15], v[14:15], v[6:7] op_sel_hi:[1,0]
	v_pk_mul_f32 v[14:15], v[14:15], v[46:47]
	global_store_dwordx4 v1, v[12:15], s[66:67] offset:1024 nt
	s_waitcnt vmcnt(7)
	v_pk_mul_f32 v[16:17], v[16:17], v[6:7] op_sel_hi:[1,0]
	v_pk_mul_f32 v[16:17], v[16:17], v[48:49]
	v_pk_mul_f32 v[18:19], v[18:19], v[6:7] op_sel_hi:[1,0]
	v_pk_mul_f32 v[18:19], v[18:19], v[50:51]
	global_store_dwordx4 v1, v[16:19], s[66:67] offset:2048 nt
	s_waitcnt vmcnt(7)
	v_pk_mul_f32 v[20:21], v[20:21], v[6:7] op_sel_hi:[1,0]
	v_pk_mul_f32 v[20:21], v[20:21], v[52:53]
	v_pk_mul_f32 v[22:23], v[22:23], v[6:7] op_sel_hi:[1,0]
	v_pk_mul_f32 v[22:23], v[22:23], v[54:55]
	global_store_dwordx4 v1, v[20:23], s[66:67] offset:3072 nt
	s_waitcnt vmcnt(7)
	v_pk_mul_f32 v[24:25], v[24:25], v[6:7] op_sel_hi:[1,0]
	v_pk_mul_f32 v[24:25], v[24:25], v[56:57]
	v_pk_mul_f32 v[26:27], v[26:27], v[6:7] op_sel_hi:[1,0]
	v_pk_mul_f32 v[26:27], v[26:27], v[58:59]
	global_store_dwordx4 v7, v[24:27], s[66:67] nt
	s_waitcnt vmcnt(7)
	v_pk_mul_f32 v[28:29], v[28:29], v[6:7] op_sel_hi:[1,0]
	v_pk_mul_f32 v[28:29], v[28:29], v[60:61]
	v_pk_mul_f32 v[30:31], v[30:31], v[6:7] op_sel_hi:[1,0]
	v_pk_mul_f32 v[30:31], v[30:31], v[62:63]
	global_store_dwordx4 v7, v[28:31], s[66:67] offset:1024 nt
	s_waitcnt vmcnt(7)
	v_pk_mul_f32 v[32:33], v[32:33], v[6:7] op_sel_hi:[1,0]
	v_pk_mul_f32 v[32:33], v[32:33], v[64:65]
	v_pk_mul_f32 v[34:35], v[34:35], v[6:7] op_sel_hi:[1,0]
	v_pk_mul_f32 v[34:35], v[34:35], v[66:67]
	global_store_dwordx4 v7, v[32:35], s[66:67] offset:2048 nt
	s_waitcnt vmcnt(7)
	v_pk_mul_f32 v[36:37], v[36:37], v[6:7] op_sel_hi:[1,0]
	v_pk_mul_f32 v[36:37], v[36:37], v[68:69]
	v_pk_mul_f32 v[38:39], v[38:39], v[6:7] op_sel_hi:[1,0]
	v_pk_mul_f32 v[38:39], v[38:39], v[70:71]
	global_store_dwordx4 v7, v[36:39], s[66:67] offset:3072 nt
	s_add_u32 s54, s54, s55
	s_cmp_lt_u32 s54, 0x3000
	s_cbranch_scc1 .Lnf_row
.Lnf_done:
.LBB0_1474:
	s_endpgm
